# scan workgroups: streaming (nt) hint on the LDS-DMA operand loads and the o stores, so the scans stop evicting the attention K/V rows from the XCD L2
# speedup vs baseline: 1.3384x; 1.0035x over previous
.Lscan_loop:
	v_readlane_b32 s56, v57, s3
	v_cvt_pk_bf16_f32 v144, v0, v1
	v_cvt_pk_bf16_f32 v145, v2, v3
	v_cvt_pk_bf16_f32 v146, v4, v5
	v_cvt_pk_bf16_f32 v147, v6, v7
	v_cvt_pk_bf16_f32 v148, v8, v9
	v_cvt_pk_bf16_f32 v149, v10, v11
	v_cvt_pk_bf16_f32 v150, v12, v13
	v_cvt_pk_bf16_f32 v151, v14, v15
	s_waitcnt lgkmcnt(7)
	v_mfma_f32_16x16x32_bf16 v[64:67], v[96:99], v[144:147], 0
	ds_read_b128 v[96:99], v93 offset:12288
	v_cvt_pk_bf16_f32 v152, v16, v17
	v_cvt_pk_bf16_f32 v153, v18, v19
	v_cvt_pk_bf16_f32 v154, v20, v21
	v_cvt_pk_bf16_f32 v155, v22, v23
	s_waitcnt lgkmcnt(7)
	v_mfma_f32_16x16x32_bf16 v[64:67], v[100:103], v[148:151], v[64:67]
	ds_read_b128 v[100:103], v93 offset:13312
	v_cvt_pk_bf16_f32 v156, v28, v29
	v_cvt_pk_bf16_f32 v157, v30, v31
	v_cvt_pk_bf16_f32 v158, v24, v25
	v_cvt_pk_bf16_f32 v159, v26, v27
	s_waitcnt lgkmcnt(7)
	v_mfma_f32_16x16x32_bf16 v[64:67], v[104:107], v[152:155], v[64:67]
	ds_read_b128 v[104:107], v93 offset:14336
	v_mul_f32_e32 v0, s56, v0
	v_mul_f32_e32 v1, s56, v1
	s_waitcnt lgkmcnt(7)
	v_mfma_f32_16x16x32_bf16 v[64:67], v[108:111], v[156:159], v[64:67]
	ds_read_b128 v[108:111], v93 offset:15360
	v_mul_f32_e32 v2, s56, v2
	v_mul_f32_e32 v3, s56, v3
	s_waitcnt lgkmcnt(7)
	v_mfma_f32_16x16x32_bf16 v[68:71], v[112:115], v[144:147], 0
	ds_read_b128 v[112:115], v93 offset:16384
	v_mul_f32_e32 v4, s56, v4
	v_mul_f32_e32 v5, s56, v5
	s_waitcnt lgkmcnt(7)
	v_mfma_f32_16x16x32_bf16 v[68:71], v[116:119], v[148:151], v[68:71]
	ds_read_b128 v[116:119], v93 offset:17408
	v_mul_f32_e32 v6, s56, v6
	v_mul_f32_e32 v7, s56, v7
	v_mfma_f32_16x16x32_bf16 v[68:71], v[120:123], v[152:155], v[68:71]
	ds_read_b128 v[120:123], v93 offset:18432
	v_mul_f32_e32 v8, s56, v8
	v_mul_f32_e32 v9, s56, v9
	v_mfma_f32_16x16x32_bf16 v[68:71], v[124:127], v[156:159], v[68:71]
	ds_read_b128 v[124:127], v93 offset:19456
	v_mul_f32_e32 v10, s56, v10
	v_mul_f32_e32 v11, s56, v11
	v_mfma_f32_16x16x32_bf16 v[72:75], v[128:131], v[144:147], 0
	ds_read_b128 v[128:131], v93 offset:20480
	v_mul_f32_e32 v12, s56, v12
	v_mul_f32_e32 v13, s56, v13
	v_mfma_f32_16x16x32_bf16 v[72:75], v[132:135], v[148:151], v[72:75]
	ds_read_b128 v[132:135], v93 offset:21504
	v_mul_f32_e32 v14, s56, v14
	v_mul_f32_e32 v15, s56, v15
	v_mfma_f32_16x16x32_bf16 v[72:75], v[136:139], v[152:155], v[72:75]
	ds_read_b128 v[136:139], v93 offset:22528
	v_mul_f32_e32 v16, s56, v16
	v_mul_f32_e32 v17, s56, v17
	v_mfma_f32_16x16x32_bf16 v[72:75], v[140:143], v[156:159], v[72:75]
	ds_read_b128 v[140:143], v93 offset:23552
	v_mul_f32_e32 v18, s56, v18
	v_mul_f32_e32 v19, s56, v19
	s_waitcnt lgkmcnt(11)
	v_mfma_f32_16x16x32_bf16 v[76:79], v[96:99], v[144:147], 0
	ds_read_b128 v[96:99], v93 offset:24576
	v_lshlrev_b32_e32 v88, 16, v172
	v_and_b32_e32 v89, 0xffff0000, v172
	v_sub_f32_e32 v64, v88, v64
	v_sub_f32_e32 v65, v89, v65
	s_waitcnt lgkmcnt(11)
	v_mfma_f32_16x16x32_bf16 v[76:79], v[100:103], v[148:151], v[76:79]
	ds_read_b128 v[100:103], v93 offset:25600
	v_lshlrev_b32_e32 v88, 16, v173
	v_and_b32_e32 v89, 0xffff0000, v173
	v_sub_f32_e32 v66, v88, v66
	v_sub_f32_e32 v67, v89, v67
	s_waitcnt lgkmcnt(11)
	v_mfma_f32_16x16x32_bf16 v[76:79], v[104:107], v[152:155], v[76:79]
	ds_read_b128 v[104:107], v93 offset:26624
	v_lshlrev_b32_e32 v88, 16, v174
	v_and_b32_e32 v89, 0xffff0000, v174
	v_sub_f32_e32 v68, v88, v68
	v_sub_f32_e32 v69, v89, v69
	s_waitcnt lgkmcnt(11)
	v_mfma_f32_16x16x32_bf16 v[76:79], v[108:111], v[156:159], v[76:79]
	ds_read_b128 v[108:111], v93 offset:27648
	v_lshlrev_b32_e32 v88, 16, v175
	v_and_b32_e32 v89, 0xffff0000, v175
	v_sub_f32_e32 v70, v88, v70
	v_sub_f32_e32 v71, v89, v71
	s_waitcnt lgkmcnt(11)
	v_mfma_f32_16x16x32_bf16 v[32:35], v[112:115], v[144:147], 0
	ds_read_b128 v[112:115], v93 offset:28672
	v_cvt_pk_bf16_f32 v80, v64, v65
	v_cvt_pk_bf16_f32 v81, v66, v67
	v_cvt_pk_bf16_f32 v82, v68, v69
	v_cvt_pk_bf16_f32 v83, v70, v71
	s_waitcnt lgkmcnt(11)
	v_mfma_f32_16x16x32_bf16 v[32:35], v[116:119], v[148:151], v[32:35]
	ds_read_b128 v[116:119], v93 offset:29696
	v_lshlrev_b32_e32 v88, 16, v176
	v_and_b32_e32 v89, 0xffff0000, v176
	v_sub_f32_e32 v72, v88, v72
	v_sub_f32_e32 v73, v89, v73
	s_waitcnt lgkmcnt(11)
	v_mfma_f32_16x16x32_bf16 v[32:35], v[120:123], v[152:155], v[32:35]
	ds_read_b128 v[120:123], v93 offset:30720
	v_lshlrev_b32_e32 v88, 16, v177
	v_and_b32_e32 v89, 0xffff0000, v177
	v_sub_f32_e32 v74, v88, v74
	v_sub_f32_e32 v75, v89, v75
	s_waitcnt lgkmcnt(11)
	v_mfma_f32_16x16x32_bf16 v[32:35], v[124:127], v[156:159], v[32:35]
	ds_read_b128 v[124:127], v93 offset:31744
	v_lshlrev_b32_e32 v88, 16, v178
	v_and_b32_e32 v89, 0xffff0000, v178
	v_sub_f32_e32 v76, v88, v76
	v_sub_f32_e32 v77, v89, v77
	s_waitcnt lgkmcnt(11)
	v_mfma_f32_16x16x32_bf16 v[36:39], v[128:131], v[144:147], 0
	ds_read_b128 v[128:131], v93 offset:32768
	v_lshlrev_b32_e32 v88, 16, v179
	v_and_b32_e32 v89, 0xffff0000, v179
	v_sub_f32_e32 v78, v88, v78
	v_sub_f32_e32 v79, v89, v79
	s_waitcnt lgkmcnt(11)
	v_mfma_f32_16x16x32_bf16 v[36:39], v[132:135], v[148:151], v[36:39]
	ds_read_b128 v[132:135], v93 offset:34816
	v_cvt_pk_bf16_f32 v84, v72, v73
	v_cvt_pk_bf16_f32 v85, v74, v75
	v_cvt_pk_bf16_f32 v86, v76, v77
	v_cvt_pk_bf16_f32 v87, v78, v79
	s_waitcnt lgkmcnt(11)
	v_mfma_f32_16x16x32_bf16 v[36:39], v[136:139], v[152:155], v[36:39]
	ds_read_b128 v[136:139], v93 offset:36864
	v_mul_f32_e32 v20, s56, v20
	s_waitcnt lgkmcnt(11)
	v_mfma_f32_16x16x32_bf16 v[36:39], v[140:143], v[156:159], v[36:39]
	ds_read_b128 v[140:143], v93 offset:37888
	v_mul_f32_e32 v21, s56, v21
	s_waitcnt lgkmcnt(11)
	v_mfma_f32_16x16x32_bf16 v[40:43], v[96:99], v[144:147], 0
	ds_read_b128 v[96:99], v93 offset:38912
	v_mul_f32_e32 v22, s56, v22
	s_waitcnt lgkmcnt(11)
	v_mfma_f32_16x16x32_bf16 v[40:43], v[100:103], v[148:151], v[40:43]
	ds_read_b128 v[100:103], v93 offset:39936
	v_mul_f32_e32 v23, s56, v23
	s_waitcnt lgkmcnt(11)
	v_mfma_f32_16x16x32_bf16 v[40:43], v[104:107], v[152:155], v[40:43]
	ds_read_b128 v[104:107], v93 offset:40960
	v_mul_f32_e32 v24, s56, v24
	s_waitcnt lgkmcnt(11)
	v_mfma_f32_16x16x32_bf16 v[40:43], v[108:111], v[156:159], v[40:43]
	ds_read_b128 v[108:111], v93 offset:41984
	v_mul_f32_e32 v25, s56, v25
	s_waitcnt lgkmcnt(11)
	v_mfma_f32_16x16x32_bf16 v[44:47], v[112:115], v[144:147], 0
	ds_read_b128 v[112:115], v93 offset:43008
	v_mul_f32_e32 v26, s56, v26
	s_waitcnt lgkmcnt(11)
	v_mfma_f32_16x16x32_bf16 v[44:47], v[116:119], v[148:151], v[44:47]
	ds_read_b128 v[116:119], v93 offset:44032
	v_mul_f32_e32 v27, s56, v27
	s_waitcnt lgkmcnt(11)
	v_mfma_f32_16x16x32_bf16 v[44:47], v[120:123], v[152:155], v[44:47]
	ds_read_b128 v[120:123], v93 offset:45056
	v_mul_f32_e32 v28, s56, v28
	s_waitcnt lgkmcnt(11)
	v_mfma_f32_16x16x32_bf16 v[44:47], v[124:127], v[156:159], v[44:47]
	ds_read_b128 v[124:127], v93 offset:46080
	v_mul_f32_e32 v29, s56, v29
	s_waitcnt lgkmcnt(11)
	v_mfma_f32_16x16x32_bf16 v[32:35], v[128:131], v[80:83], v[32:35]
	ds_read_b128 v[128:131], v93 offset:47104
	v_mul_f32_e32 v30, s56, v30
	s_waitcnt lgkmcnt(11)
	v_mfma_f32_16x16x32_bf16 v[36:39], v[132:135], v[80:83], v[36:39]
	ds_read_b128 v[132:135], v93 offset:48128
	v_mul_f32_e32 v31, s56, v31
	s_waitcnt lgkmcnt(11)
	v_mfma_f32_16x16x32_bf16 v[40:43], v[136:139], v[80:83], v[40:43]
	ds_read_b128 v[136:139], v93 offset:49152
	s_waitcnt lgkmcnt(11)
	v_mfma_f32_16x16x32_bf16 v[40:43], v[140:143], v[84:87], v[40:43]
	ds_read_b128 v[140:143], v93 offset:50176
	s_waitcnt lgkmcnt(11)
	v_mfma_f32_16x16x32_bf16 v[44:47], v[96:99], v[80:83], v[44:47]
	ds_read_b128 v[96:99], v93 offset:51200
	s_waitcnt lgkmcnt(11)
	v_mfma_f32_16x16x32_bf16 v[44:47], v[100:103], v[84:87], v[44:47]
	ds_read_b128 v[100:103], v93 offset:52224
	s_waitcnt lgkmcnt(11)
	v_mfma_f32_16x16x32_bf16 v[0:3], v[104:107], v[80:83], v[0:3]
	ds_read_b128 v[104:107], v93 offset:53248
	s_waitcnt lgkmcnt(11)
	v_mfma_f32_16x16x32_bf16 v[0:3], v[108:111], v[84:87], v[0:3]
	ds_read_b128 v[108:111], v93 offset:54272
	s_waitcnt lgkmcnt(11)
	v_mfma_f32_16x16x32_bf16 v[4:7], v[112:115], v[80:83], v[4:7]
	ds_read_b128 v[112:115], v93 offset:55296
	s_mov_b64 vcc, s[16:17]
	v_cndmask_b32_dpp v200, v33, v32, vcc quad_perm:[1,0,3,2] row_mask:0xf bank_mask:0xf
	v_cndmask_b32_dpp v202, v35, v34, vcc quad_perm:[1,0,3,2] row_mask:0xf bank_mask:0xf
	v_cndmask_b32_dpp v204, v37, v36, vcc quad_perm:[1,0,3,2] row_mask:0xf bank_mask:0xf
	v_cndmask_b32_dpp v206, v39, v38, vcc quad_perm:[1,0,3,2] row_mask:0xf bank_mask:0xf
	s_waitcnt lgkmcnt(11)
	v_mfma_f32_16x16x32_bf16 v[4:7], v[116:119], v[84:87], v[4:7]
	ds_read_b128 v[116:119], v93 offset:56320
	s_mov_b64 vcc, s[18:19]
	v_cndmask_b32_dpp v201, v32, v33, vcc quad_perm:[1,0,3,2] row_mask:0xf bank_mask:0xf
	v_cndmask_b32_dpp v203, v34, v35, vcc quad_perm:[1,0,3,2] row_mask:0xf bank_mask:0xf
	v_cndmask_b32_dpp v205, v36, v37, vcc quad_perm:[1,0,3,2] row_mask:0xf bank_mask:0xf
	v_cndmask_b32_dpp v207, v38, v39, vcc quad_perm:[1,0,3,2] row_mask:0xf bank_mask:0xf
	s_waitcnt lgkmcnt(11)
	v_mfma_f32_16x16x32_bf16 v[8:11], v[120:123], v[80:83], v[8:11]
	s_mov_b64 vcc, s[20:21]
	v_cndmask_b32_dpp v52, v202, v200, vcc quad_perm:[2,3,0,1] row_mask:0xf bank_mask:0xf
	v_cndmask_b32_dpp v53, v203, v201, vcc quad_perm:[2,3,0,1] row_mask:0xf bank_mask:0xf
	v_cndmask_b32_dpp v58, v206, v204, vcc quad_perm:[2,3,0,1] row_mask:0xf bank_mask:0xf
	v_cndmask_b32_dpp v59, v207, v205, vcc quad_perm:[2,3,0,1] row_mask:0xf bank_mask:0xf
	v_add_u32_e32 v93, s8, v93
	v_add_u32_e32 v94, s8, v94
	s_sub_i32 s8, 0, s8
	s_waitcnt lgkmcnt(10)
	v_mfma_f32_16x16x32_bf16 v[8:11], v[124:127], v[84:87], v[8:11]
	s_mov_b64 vcc, s[22:23]
	v_cndmask_b32_dpp v54, v200, v202, vcc quad_perm:[2,3,0,1] row_mask:0xf bank_mask:0xf
	v_cndmask_b32_dpp v55, v201, v203, vcc quad_perm:[2,3,0,1] row_mask:0xf bank_mask:0xf
	v_cndmask_b32_dpp v60, v204, v206, vcc quad_perm:[2,3,0,1] row_mask:0xf bank_mask:0xf
	v_cndmask_b32_dpp v61, v205, v207, vcc quad_perm:[2,3,0,1] row_mask:0xf bank_mask:0xf
	s_waitcnt lgkmcnt(9)
	v_mfma_f32_16x16x32_bf16 v[12:15], v[128:131], v[80:83], v[12:15]
	global_store_dwordx4 v190, v[52:55], s[14:15] nt
	global_store_dwordx4 v191, v[58:61], s[14:15] nt
	s_mov_b64 vcc, s[16:17]
	v_cndmask_b32_dpp v208, v41, v40, vcc quad_perm:[1,0,3,2] row_mask:0xf bank_mask:0xf
	v_cndmask_b32_dpp v210, v43, v42, vcc quad_perm:[1,0,3,2] row_mask:0xf bank_mask:0xf
	v_cndmask_b32_dpp v212, v45, v44, vcc quad_perm:[1,0,3,2] row_mask:0xf bank_mask:0xf
	v_cndmask_b32_dpp v214, v47, v46, vcc quad_perm:[1,0,3,2] row_mask:0xf bank_mask:0xf
	s_waitcnt lgkmcnt(8)
	v_mfma_f32_16x16x32_bf16 v[12:15], v[132:135], v[84:87], v[12:15]
	s_mov_b64 vcc, s[18:19]
	v_cndmask_b32_dpp v209, v40, v41, vcc quad_perm:[1,0,3,2] row_mask:0xf bank_mask:0xf
	v_cndmask_b32_dpp v211, v42, v43, vcc quad_perm:[1,0,3,2] row_mask:0xf bank_mask:0xf
	v_cndmask_b32_dpp v213, v44, v45, vcc quad_perm:[1,0,3,2] row_mask:0xf bank_mask:0xf
	v_cndmask_b32_dpp v215, v46, v47, vcc quad_perm:[1,0,3,2] row_mask:0xf bank_mask:0xf
	s_waitcnt lgkmcnt(7)
	v_mfma_f32_16x16x32_bf16 v[16:19], v[136:139], v[80:83], v[16:19]
	s_mov_b64 vcc, s[20:21]
	v_cndmask_b32_dpp v220, v210, v208, vcc quad_perm:[2,3,0,1] row_mask:0xf bank_mask:0xf
	v_cndmask_b32_dpp v221, v211, v209, vcc quad_perm:[2,3,0,1] row_mask:0xf bank_mask:0xf
	v_cndmask_b32_dpp v224, v214, v212, vcc quad_perm:[2,3,0,1] row_mask:0xf bank_mask:0xf
	v_cndmask_b32_dpp v225, v215, v213, vcc quad_perm:[2,3,0,1] row_mask:0xf bank_mask:0xf
	s_waitcnt lgkmcnt(6)
	v_mfma_f32_16x16x32_bf16 v[16:19], v[140:143], v[84:87], v[16:19]
	s_mov_b64 vcc, s[22:23]
	v_cndmask_b32_dpp v222, v208, v210, vcc quad_perm:[2,3,0,1] row_mask:0xf bank_mask:0xf
	v_cndmask_b32_dpp v223, v209, v211, vcc quad_perm:[2,3,0,1] row_mask:0xf bank_mask:0xf
	v_cndmask_b32_dpp v226, v212, v214, vcc quad_perm:[2,3,0,1] row_mask:0xf bank_mask:0xf
	v_cndmask_b32_dpp v227, v213, v215, vcc quad_perm:[2,3,0,1] row_mask:0xf bank_mask:0xf
	s_nop 0
	global_store_dwordx4 v192, v[220:223], s[14:15] nt
	global_store_dwordx4 v193, v[224:227], s[14:15] nt
	s_waitcnt lgkmcnt(0)
	s_waitcnt vmcnt(4)
	s_barrier
	ds_read_b128 v[120:123], v93 offset:6144
	ds_read_b128 v[124:127], v93 offset:7168
	ds_read_b128 v[128:131], v93 offset:8192
	ds_read_b128 v[132:135], v93 offset:9216
	ds_read_b128 v[136:139], v93 offset:10240
	ds_read_b128 v[140:143], v93 offset:11264
	v_mfma_f32_16x16x32_bf16 v[20:23], v[96:99], v[80:83], v[20:23]
	ds_read_b128 v[96:99], v93
	v_mfma_f32_16x16x32_bf16 v[20:23], v[100:103], v[84:87], v[20:23]
	ds_read_b128 v[100:103], v93 offset:1024
	v_mfma_f32_16x16x32_bf16 v[28:31], v[104:107], v[80:83], v[28:31]
	ds_read_b128 v[104:107], v93 offset:2048
	v_mfma_f32_16x16x32_bf16 v[28:31], v[108:111], v[84:87], v[28:31]
	ds_read_b128 v[108:111], v93 offset:3072
	v_mfma_f32_16x16x32_bf16 v[24:27], v[112:115], v[80:83], v[24:27]
	ds_read_b128 v[112:115], v93 offset:4096
	v_mfma_f32_16x16x32_bf16 v[24:27], v[116:119], v[84:87], v[24:27]
	ds_read_b128 v[116:119], v93 offset:5120
	ds_read2st64_b64 v[172:175], v94 offset0:112 offset1:113
	ds_read2st64_b64 v[176:179], v94 offset0:114 offset1:115
	s_cmp_gt_u32 s3, 29
	s_cbranch_scc1 .Lscan_nodma
	s_add_i32 s0, s9, s6
	s_add_i32 m0, s0, 0x0
	s_nop 0
	global_load_lds_dwordx4 v48, s[10:11] nt
	s_add_i32 m0, s0, 0x2000
	s_nop 0
	global_load_lds_dwordx4 v181, s[10:11] nt
	s_add_i32 m0, s0, 0x4000
	s_nop 0
	global_load_lds_dwordx4 v182, s[10:11] nt
	s_add_i32 m0, s0, 0x6000
	s_nop 0
	global_load_lds_dwordx4 v183, s[10:11] nt
	s_add_i32 m0, s0, 0x8000
	s_nop 0
	global_load_lds_dwordx4 v184, s[10:11] nt
	s_add_i32 m0, s0, 0xa000
	s_nop 0
	global_load_lds_dwordx4 v185, s[10:11] nt
	s_add_i32 m0, s0, 0xc000
	s_nop 0
	global_load_lds_dwordx4 v186, s[10:11] nt
	s_add_i32 m0, s0, 0xe000
	s_nop 0
	global_load_lds_dwordx4 v48, s[12:13] nt
	s_add_i32 m0, s0, 0x10000
	s_nop 0
	global_load_lds_dwordx4 v181, s[12:13] nt
	s_add_u32 s10, s10, 0xe000
	s_addc_u32 s11, s11, 0
	s_add_u32 s12, s12, 0x4000
	s_addc_u32 s13, s13, 0
